# w_up int8 transpose loop paced: s_sleep 25 between the row-load issue (+ column-step division) and the k-scale loads
# baseline (speedup 1.0000x reference)
; __device__ __forceinline__ void ph_transpose_q8(const TrJob job, LAS unsigned* scr, int gw, int NGW, int lane) {
;     ...
;     for (int item = gw; item < nitems; item += NGW) {
;         const int kb = item / ngrp, gq = item % ngrp, k0 = 64 * kb, r0 = 64 * gq, sb = srcbase_of(job.kind, r0);
;     ...
;           for (int i = 0; i < 4; ++i) { const int kq = 4 * i + (lane >> 4);
; #pragma unroll
;               for (int q = 0; q < 4; ++q) { const int k = k0 + 4 * kq + q; kv[i][q] = (ks && k < job.kscale_n) ? ks[k] : 1.f; } }
.Lq8u_div_done:
	s_or_b64 exec, exec, s[56:57]
	s_sleep 25
	v_cmp_gt_i32_e32 vcc, s41, v76
	s_and_b64 s[10:11], s[18:19], vcc
	v_mov_b32_e32 v78, 1.0
	v_ashrrev_i32_e32 v77, 31, v76
	v_mov_b32_e32 v80, 1.0
	s_and_saveexec_b64 s[6:7], s[10:11]
	s_cbranch_execz .LBB0_878
	v_lshl_add_u64 v[108:109], v[76:77], 2, s[16:17]
	global_load_dword v80, v[108:109], off
